# attention prep: v row, indexer-query rows and K-quarter partials also loaded at the top of the token iteration
# speedup vs baseline: 1.0068x; 1.0068x over previous
; __device__ __forceinline__ void prep_phase(const int TID, const int BID, PP p) {
;     ...
;         const bf16_t* r = raw + (size_t)tok * NINP; const int pos = tok & 4095;
;         float cq[4], sq[4], ci[4], si[4];
;         { const int j = lane & 3, ji = lane & 1;
; #pragma unroll
;           for (int e = 0; e < 4; ++e) {
;               rope_cs(pos, exp2f(-(float)(4 * j + e) * (L2T / 16.0f)), cq[e], sq[e]);
;               rope_cs(pos, exp2f(-(float)(4 * ji + e) * (L2T / 8.0f)), ci[e], si[e]); } }
; #pragma unroll
;         for (int it = 0; it < 10; ++it) {
;             const int head = 2 * it + (lane >> 5), j = lane & 31;
;             const bool isq = head < 16;
;             const int col = isq ? head * 128 : 2048 + (head - 16) * 128;
;             const u32x2 rw = *(const u32x2*)(r + col + 4 * j);
;             f32x4 v = (f32x4){bf_lo(rw.x), bf_hi(rw.x), bf_lo(rw.y), bf_hi(rw.y)};
;             float ss = v[0] * v[0] + v[1] * v[1] + v[2] * v[2] + v[3] * v[3];
; #pragma unroll
;             for (int o = 16; o > 0; o >>= 1) ss += __shfl_xor(ss, o);
;             const float rn = rinv_of(ss, 1.0f / 128.0f);
;             const f32x4 g4 = *(const f32x4*)((isq ? p->attn_q_gain : p->attn_k_gain) + 4 * j);
;             v = v * rn * g4;
;             f32x4 pt;
; #pragma unroll
;             for (int e = 0; e < 4; ++e) pt[e] = __shfl_xor(v[e], 4);
;             if (j < 8) {
; #pragma unroll
;                 for (int e = 0; e < 4; ++e) v[e] = (j < 4) ? v[e] * cq[e] - pt[e] * sq[e] : v[e] * cq[e] + pt[e] * sq[e];
;             }
;             u32x2 o; o.x = cvt_pk_bf16(v[0], v[1]); o.y = cvt_pk_bf16(v[2], v[3]);
;             { int w8 = __builtin_amdgcn_cvt_pk_fp8_f32(v[0], v[1], 0, false); w8 = __builtin_amdgcn_cvt_pk_fp8_f32(v[2], v[3], w8, true);
;               if (isq) *(int*)((unsigned char*)Qb + (size_t)tok * 2048 + head * 128 + 4 * j) = w8;
;               else *(int*)((unsigned char*)Kb + (size_t)tok * 512 + (head - 16) * 128 + 4 * j) = w8; }
;         }
;         { const u32x4 vw = *(const u32x4*)(r + 2560 + 8 * lane);
;           int lo = __builtin_amdgcn_cvt_pk_fp8_f32(bf_lo(vw.x), bf_hi(vw.x), 0, false); lo = __builtin_amdgcn_cvt_pk_fp8_f32(bf_lo(vw.y), bf_hi(vw.y), lo, true);
;           int hi = __builtin_amdgcn_cvt_pk_fp8_f32(bf_lo(vw.z), bf_hi(vw.z), 0, false); hi = __builtin_amdgcn_cvt_pk_fp8_f32(bf_lo(vw.w), bf_hi(vw.w), hi, true);
.LBB0_748:
	v_and_b32_e32 v40, 0xfff, v62
	v_cvt_f64_u32_e32 v[40:41], v40
	s_mov_b32 s0, 0x6dc9c883
	v_mul_f64 v[42:43], v[0:1], v[40:41]
	s_mov_b32 s1, 0x3fc45f30
	v_mul_f64 v[44:45], v[42:43], s[0:1]
	v_rndne_f64_e32 v[44:45], v[44:45]
	v_fma_f64 v[42:43], v[42:43], s[0:1], -v[44:45]
	v_mul_f64 v[44:45], v[4:5], v[40:41]
	v_mul_f64 v[48:49], v[44:45], s[0:1]
	v_rndne_f64_e32 v[48:49], v[48:49]
	v_fma_f64 v[44:45], v[44:45], s[0:1], -v[48:49]
	v_cvt_f32_f64_e32 v42, v[42:43]
	v_cvt_f32_f64_e32 v43, v[44:45]
	v_mul_f64 v[44:45], v[8:9], v[40:41]
	v_mul_f64 v[50:51], v[12:13], v[40:41]
	v_mul_f64 v[48:49], v[44:45], s[0:1]
	s_waitcnt lgkmcnt(0)
	v_mul_f64 v[52:53], v[50:51], s[0:1]
	v_rndne_f64_e32 v[48:49], v[48:49]
	v_rndne_f64_e32 v[52:53], v[52:53]
	v_fma_f64 v[44:45], v[44:45], s[0:1], -v[48:49]
	v_fma_f64 v[50:51], v[50:51], s[0:1], -v[52:53]
	v_cvt_f32_f64_e32 v44, v[44:45]
	v_cvt_f32_f64_e32 v45, v[50:51]
	v_lshl_add_u64 v[50:51], s[2:3], 0, v[26:27]
	s_mov_b32 s0, 0x1b500000
	v_add_co_u32_e32 v54, vcc, s0, v50
	v_sin_f32_e32 v46, v42
	s_nop 0
	v_addc_co_u32_e32 v55, vcc, 0, v51, vcc
	global_load_dwordx2 v[56:57], v[54:55], off
	v_readlane_b32 s26, v254, 15
	v_readlane_b32 s27, v254, 16
	v_mbcnt_lo_u32_b32 v216, -1, 0
	v_mbcnt_hi_u32_b32 v216, -1, v216
	v_lshlrev_b32_e32 v216, 3, v216
	v_mov_b32_e32 v217, 0
	s_mov_b64 s[28:29], 0x2000
	v_lshl_add_u64 v[212:213], v[54:55], 0, s[26:27]
	v_lshl_add_u64 v[212:213], v[212:213], 0, v[216:217]
	v_lshl_add_u64 v[214:215], v[212:213], 0, s[28:29]
	global_load_dwordx4 v[208:211], v[212:213], off
	global_load_dwordx4 v[208:211], v[212:213], off offset:1024
	global_load_dwordx4 v[208:211], v[212:213], off offset:2048
	global_load_dwordx4 v[208:211], v[212:213], off offset:3072
	global_load_dwordx4 v[208:211], v[214:215], off offset:-4096
	global_load_dwordx4 v[208:211], v[214:215], off offset:-3072
	global_load_dwordx4 v[208:211], v[214:215], off offset:-2048
	global_load_dwordx4 v[208:211], v[214:215], off offset:-1024
	global_load_dwordx4 v[208:211], v[214:215], off
	s_mov_b64 s[30:31], 0x1000
	global_load_dwordx4 v[236:239], v[16:17], off
	global_load_dwordx2 v[218:219], v[54:55], off offset:512
	global_load_dwordx2 v[220:221], v[54:55], off offset:1024
	global_load_dwordx2 v[222:223], v[54:55], off offset:1536
	global_load_dwordx2 v[224:225], v[54:55], off offset:2048
	global_load_dwordx2 v[226:227], v[54:55], off offset:2560
	global_load_dwordx2 v[228:229], v[54:55], off offset:3072
	global_load_dwordx2 v[230:231], v[54:55], off offset:3584
	v_lshl_add_u64 v[240:241], v[54:55], 0, s[30:31]
	global_load_dwordx2 v[232:233], v[240:241], off
	global_load_dwordx2 v[234:235], v[240:241], off offset:512
	v_lshl_add_u64 v[242:243], s[2:3], 0, v[30:31]
	global_load_dwordx4 v[108:111], v[242:243], off
	v_lshl_add_u64 v[242:243], s[2:3], 0, v[32:33]
	global_load_dwordx2 v[100:101], v[242:243], off offset:-1024
	global_load_dwordx2 v[102:103], v[242:243], off offset:-512
	global_load_dwordx2 v[104:105], v[242:243], off
	global_load_dwordx2 v[106:107], v[242:243], off offset:512
	v_lshl_add_u64 v[242:243], s[2:3], 0, v[22:23]
	s_mov_b64 s[30:31], 0x27f04000
	v_lshl_add_u64 v[244:245], v[242:243], 0, s[30:31]
	global_load_dwordx4 v[112:115], v[244:245], off
	s_mov_b64 s[30:31], 0x28704000
	v_lshl_add_u64 v[244:245], v[242:243], 0, s[30:31]
	global_load_dwordx4 v[116:119], v[244:245], off
	s_mov_b64 s[30:31], 0x28f04000
	v_lshl_add_u64 v[244:245], v[242:243], 0, s[30:31]
	global_load_dwordx4 v[120:123], v[244:245], off
	s_mov_b64 s[30:31], 0x29704000
	v_lshl_add_u64 v[244:245], v[242:243], 0, s[30:31]
	global_load_dwordx4 v[124:127], v[244:245], off
	s_and_saveexec_b64 s[34:35], s[16:17]
	v_lshl_add_u64 v[242:243], s[2:3], 0, v[24:25]
	s_mov_b64 s[30:31], 0x27f04000
	v_lshl_add_u64 v[244:245], v[242:243], 0, s[30:31]
	global_load_dword v128, v[244:245], off offset:256
	s_mov_b64 s[30:31], 0x28704000
	v_lshl_add_u64 v[244:245], v[242:243], 0, s[30:31]
	global_load_dword v129, v[244:245], off offset:256
	s_mov_b64 s[30:31], 0x28f04000
	v_lshl_add_u64 v[244:245], v[242:243], 0, s[30:31]
	global_load_dword v130, v[244:245], off offset:256
	s_mov_b64 s[30:31], 0x29704000
	v_lshl_add_u64 v[244:245], v[242:243], 0, s[30:31]
	global_load_dword v131, v[244:245], off offset:256
	s_mov_b64 exec, s[34:35]
	v_cos_f32_e32 v42, v42
	v_sin_f32_e32 v47, v43
	v_cos_f32_e32 v43, v43
	v_sin_f32_e32 v48, v44
	v_cos_f32_e32 v44, v44
	v_sin_f32_e32 v49, v45
	v_cos_f32_e32 v45, v45
	s_waitcnt vmcnt(0)
	v_lshlrev_b32_e32 v60, 16, v56
	v_and_b32_e32 v61, 0xffff0000, v56
	v_and_b32_e32 v52, 0xffff0000, v57
	v_pk_mul_f32 v[58:59], v[60:61], v[60:61]
	v_and_b32_e32 v53, s0, v57
	v_lshlrev_b32_e32 v57, 16, v57
	v_mov_b32_e32 v56, v52
	v_pk_mul_f32 v[68:69], v[56:57], v[56:57]
	v_add_f32_e32 v58, v58, v59
	v_add_f32_e32 v58, v69, v58
	v_add_f32_e32 v58, v68, v58
	v_mov_b64_e32 v[68:69], v[236:237]
	v_mov_b64_e32 v[70:71], v[238:239]
	ds_bpermute_b32 v59, v64, v58
	v_pk_mov_b32 v[52:53], v[56:57], v[52:53] op_sel:[1,0]
	s_waitcnt lgkmcnt(0)
	v_add_f32_e32 v58, v58, v59
	s_nop 1
	v_add_f32_dpp v58, v58, v58 row_ror:8 row_mask:0xf bank_mask:0xf
	s_nop 1
	v_add_f32_dpp v58, v58, v58 row_ror:4 row_mask:0xf bank_mask:0xf
	s_nop 1
	v_add_f32_dpp v58, v58, v58 row_ror:2 row_mask:0xf bank_mask:0xf
	s_nop 1
	v_add_f32_dpp v58, v58, v58 row_ror:1 row_mask:0xf bank_mask:0xf
	v_fmamk_f32 v58, v58, 0x3c000000, v189
	v_cmp_gt_f32_e32 vcc, s78, v58
	v_mul_f32_e32 v59, 0x4b800000, v58
	s_nop 0
	v_cndmask_b32_e32 v58, v58, v59, vcc
	v_rsq_f32_e32 v58, v58
	s_nop 0
	v_mul_f32_e32 v59, 0x45800000, v58
	v_cndmask_b32_e32 v58, v58, v59, vcc
	v_pk_mul_f32 v[60:61], v[58:59], v[60:61] op_sel_hi:[0,1]
	v_pk_mul_f32 v[52:53], v[58:59], v[52:53] op_sel_hi:[0,1]
	v_pk_mul_f32 v[52:53], v[70:71], v[52:53]
	v_pk_mul_f32 v[56:57], v[68:69], v[60:61]
	ds_bpermute_b32 v60, v63, v56
	ds_bpermute_b32 v61, v63, v57
	ds_bpermute_b32 v58, v63, v52
	ds_bpermute_b32 v59, v63, v53
	s_and_saveexec_b64 s[22:23], s[8:9]
	s_cbranch_execz .LBB0_750
	s_waitcnt lgkmcnt(2)
	v_pk_mul_f32 v[60:61], v[46:47], v[60:61]
	s_waitcnt lgkmcnt(0)
	v_pk_mul_f32 v[58:59], v[48:49], v[58:59]
	v_cndmask_b32_e64 v61, v61, -v61, s[10:11]
	v_cndmask_b32_e64 v60, v60, -v60, s[10:11]
	v_cndmask_b32_e64 v59, v59, -v59, s[10:11]
	v_cndmask_b32_e64 v58, v58, -v58, s[10:11]
	v_pk_fma_f32 v[56:57], v[42:43], v[56:57], v[60:61]
	v_pk_fma_f32 v[52:53], v[44:45], v[52:53], v[58:59]

; __device__ __forceinline__ unsigned cvt_pk_bf16(float lo, float hi) { unsigned r; asm volatile("v_cvt_pk_bf16_f32 %0, %1, %2" : "=v"(r) : "v"(lo), "v"(hi)); return r; }
; __device__ __forceinline__ float bf_lo(unsigned v) { return __uint_as_float(v << 16); }
; __device__ __forceinline__ float bf_hi(unsigned v) { return __uint_as_float(v & 0xffff0000u); }
; __device__ __forceinline__ void prep_phase(const int TID, const int BID, PP p) {
;     ...
;               rope_cs(pos, exp2f(-(float)(4 * j + e) * (L2T / 16.0f)), cq[e], sq[e]);
;               rope_cs(pos, exp2f(-(float)(4 * ji + e) * (L2T / 8.0f)), ci[e], si[e]); } }
;     ...
;         { const u32x4 vw = *(const u32x4*)(r + 2560 + 8 * lane);
;           int lo = __builtin_amdgcn_cvt_pk_fp8_f32(bf_lo(vw.x), bf_hi(vw.x), 0, false); lo = __builtin_amdgcn_cvt_pk_fp8_f32(bf_lo(vw.y), bf_hi(vw.y), lo, true);
;           int hi = __builtin_amdgcn_cvt_pk_fp8_f32(bf_lo(vw.z), bf_hi(vw.z), 0, false); hi = __builtin_amdgcn_cvt_pk_fp8_f32(bf_lo(vw.w), bf_hi(vw.w), hi, true);
;           *(u32x2*)((unsigned char*)Vb + (size_t)tok * 512 + 8 * lane) = (u32x2){(unsigned)lo, (unsigned)hi}; }
; #pragma unroll
;         for (int it = 0; it < 5; ++it) {
;             const int j = lane & 15;
;             const int head = 4 * it + (lane >> 4);
;             const int col = (it < 4) ? 3072 + head * 64 : 4096;
;             f32x4 v;
;             if (it < 4) { const u32x2 rw = *(const u32x2*)(r + col + 4 * j); v = (f32x4){bf_lo(rw.x), bf_hi(rw.x), bf_lo(rw.y), bf_hi(rw.y)}; }
;             else { const float* rt = rawt + (size_t)tok * 256 + 4 * j; v = *(const f32x4*)rt + *(const f32x4*)(rt + (size_t)T * 256) + *(const f32x4*)(rt + (size_t)2 * T * 256) + *(const f32x4*)(rt + (size_t)3 * T * 256); }
;             f32x4 pt;
; #pragma unroll
;             for (int e = 0; e < 4; ++e) pt[e] = __shfl_xor(v[e], 2);
;             if (j < 4) {
; #pragma unroll
;                 for (int e = 0; e < 4; ++e) v[e] = (j < 2) ? v[e] * ci[e] - pt[e] * si[e] : v[e] * ci[e] + pt[e] * si[e];
;             }
;             u32x2 o; o.x = cvt_pk_bf16(v[0], v[1]); o.y = cvt_pk_bf16(v[2], v[3]);
;             if (it < 4) *(u32x2*)(QIb + (size_t)tok * 1024 + head * 64 + 4 * j) = o;
.LBB0_768:
	s_or_b64 exec, exec, s[22:23]
	s_mov_b32 s0, 0x6dc9c883
	v_mul_f64 v[42:43], v[2:3], v[40:41]
	s_mov_b32 s1, 0x3fc45f30
	v_mul_f64 v[44:45], v[42:43], s[0:1]
	v_rndne_f64_e32 v[44:45], v[44:45]
	v_fma_f64 v[42:43], v[42:43], s[0:1], -v[44:45]
	v_mul_f64 v[44:45], v[6:7], v[40:41]
	v_mul_f64 v[48:49], v[44:45], s[0:1]
	v_rndne_f64_e32 v[48:49], v[48:49]
	v_fma_f64 v[44:45], v[44:45], s[0:1], -v[48:49]
	v_cvt_f32_f64_e32 v42, v[42:43]
	v_cvt_f32_f64_e32 v43, v[44:45]
	v_mul_f64 v[44:45], v[10:11], v[40:41]
	v_mul_f64 v[40:41], v[14:15], v[40:41]
	s_waitcnt lgkmcnt(0)
	v_mul_f64 v[56:57], v[40:41], s[0:1]
	v_mul_f64 v[48:49], v[44:45], s[0:1]
	v_rndne_f64_e32 v[56:57], v[56:57]
	v_rndne_f64_e32 v[48:49], v[48:49]
	v_fma_f64 v[40:41], v[40:41], s[0:1], -v[56:57]
	v_fma_f64 v[44:45], v[44:45], s[0:1], -v[48:49]
	v_cvt_f32_f64_e32 v40, v[40:41]
	v_cvt_f32_f64_e32 v44, v[44:45]
	v_sin_f32_e32 v49, v40
	v_cos_f32_e32 v45, v40
	v_cvt_pk_bf16_f32 v40, v54, v55
	v_sin_f32_e32 v46, v42
	v_cvt_pk_bf16_f32 v40, v50, v51
	v_cos_f32_e32 v42, v42
	v_mov_b32_e32 v40, v161
	v_cvt_pk_fp8_f32 v40, v54, v55
	v_sin_f32_e32 v47, v43
	v_cos_f32_e32 v43, v43
	v_sin_f32_e32 v48, v44
	v_cvt_pk_fp8_f32 v40, v50, v51 op_sel:[0,0,1]
	v_cos_f32_e32 v44, v44
	global_store_dword v[52:53], v40, off offset:256
	v_lshl_add_u64 v[40:41], s[2:3], 0, v[30:31]
	v_mov_b64_e32 v[50:51], v[108:109]
	v_mov_b64_e32 v[52:53], v[110:111]
	v_mov_b32_e32 v40, v161
	v_lshlrev_b32_e32 v41, 16, v50
	v_and_b32_e32 v50, 0xffff0000, v50
	v_cvt_pk_fp8_f32 v40, v41, v50
	v_lshlrev_b32_e32 v41, 16, v51
	v_and_b32_e32 v50, 0xffff0000, v51
	v_and_b32_e32 v51, 0xffff0000, v52
	v_cvt_pk_fp8_f32 v40, v41, v50 op_sel:[0,0,1]
	v_lshlrev_b32_e32 v50, 16, v52
	v_mov_b32_e32 v41, v161
	v_cvt_pk_fp8_f32 v41, v50, v51
	v_lshlrev_b32_e32 v50, 16, v53
	v_and_b32_e32 v51, 0xffff0000, v53
	v_cvt_pk_fp8_f32 v41, v50, v51 op_sel:[0,0,1]
	v_lshl_add_u64 v[50:51], s[2:3], 0, v[36:37]
	global_store_dwordx2 v[50:51], v[40:41], off
	v_lshl_add_u64 v[40:41], s[2:3], 0, v[32:33]
	v_mov_b64_e32 v[54:55], v[100:101]
	v_lshlrev_b32_e32 v50, 16, v55
	v_and_b32_e32 v51, 0xffff0000, v55
	v_lshlrev_b32_e32 v52, 16, v54
	v_and_b32_e32 v53, 0xffff0000, v54
	ds_bpermute_b32 v56, v66, v52
	ds_bpermute_b32 v57, v66, v53
	ds_bpermute_b32 v54, v66, v50
	ds_bpermute_b32 v55, v66, v51
	s_and_saveexec_b64 s[22:23], s[12:13]
	s_cbranch_execz .LBB0_770
	s_waitcnt lgkmcnt(2)
	v_pk_mul_f32 v[56:57], v[46:47], v[56:57]
	s_waitcnt lgkmcnt(0)
	v_pk_mul_f32 v[54:55], v[48:49], v[54:55]
	v_cndmask_b32_e64 v57, v57, -v57, s[14:15]
	v_cndmask_b32_e64 v56, v56, -v56, s[14:15]
	v_cndmask_b32_e64 v55, v55, -v55, s[14:15]
	v_cndmask_b32_e64 v54, v54, -v54, s[14:15]
	v_pk_fma_f32 v[52:53], v[42:43], v[52:53], v[56:57]
	v_pk_fma_f32 v[50:51], v[44:45], v[50:51], v[54:55]
.LBB0_770:
	s_or_b64 exec, exec, s[22:23]
	v_cvt_pk_bf16_f32 v52, v52, v53
	v_cvt_pk_bf16_f32 v53, v50, v51
	v_lshl_add_u64 v[50:51], s[2:3], 0, v[28:29]
	global_store_dwordx2 v[50:51], v[52:53], off offset:-1024
	s_waitcnt lgkmcnt(2)
	v_mov_b64_e32 v[56:57], v[102:103]
	v_lshlrev_b32_e32 v52, 16, v57
	v_and_b32_e32 v53, 0xffff0000, v57
	s_waitcnt lgkmcnt(1)
	v_lshlrev_b32_e32 v54, 16, v56
	s_waitcnt lgkmcnt(0)
	v_and_b32_e32 v55, 0xffff0000, v56
	ds_bpermute_b32 v58, v66, v54
	ds_bpermute_b32 v59, v66, v55
	ds_bpermute_b32 v56, v66, v52
	ds_bpermute_b32 v57, v66, v53
	s_and_saveexec_b64 s[22:23], s[12:13]
	s_cbranch_execz .LBB0_772
	s_waitcnt lgkmcnt(2)
	v_pk_mul_f32 v[58:59], v[46:47], v[58:59]
	s_waitcnt lgkmcnt(0)
	v_pk_mul_f32 v[56:57], v[48:49], v[56:57]
	v_cndmask_b32_e64 v59, v59, -v59, s[14:15]
	v_cndmask_b32_e64 v58, v58, -v58, s[14:15]
	v_cndmask_b32_e64 v57, v57, -v57, s[14:15]
	v_cndmask_b32_e64 v56, v56, -v56, s[14:15]
	v_pk_fma_f32 v[54:55], v[42:43], v[54:55], v[58:59]
	v_pk_fma_f32 v[52:53], v[44:45], v[52:53], v[56:57]
; __device__ __forceinline__ unsigned cvt_pk_bf16(float lo, float hi) { unsigned r; asm volatile("v_cvt_pk_bf16_f32 %0, %1, %2" : "=v"(r) : "v"(lo), "v"(hi)); return r; }
; __device__ __forceinline__ float bf_lo(unsigned v) { return __uint_as_float(v << 16); }
; __device__ __forceinline__ float bf_hi(unsigned v) { return __uint_as_float(v & 0xffff0000u); }
; __device__ __forceinline__ void prep_phase(const int TID, const int BID, PP p) {
;     ...
;         for (int it = 0; it < 5; ++it) {
;             const int j = lane & 15;
;             const int head = 4 * it + (lane >> 4);
;             const int col = (it < 4) ? 3072 + head * 64 : 4096;
;             f32x4 v;
;             if (it < 4) { const u32x2 rw = *(const u32x2*)(r + col + 4 * j); v = (f32x4){bf_lo(rw.x), bf_hi(rw.x), bf_lo(rw.y), bf_hi(rw.y)}; }
;             else { const float* rt = rawt + (size_t)tok * 256 + 4 * j; v = *(const f32x4*)rt + *(const f32x4*)(rt + (size_t)T * 256) + *(const f32x4*)(rt + (size_t)2 * T * 256) + *(const f32x4*)(rt + (size_t)3 * T * 256); }
;             f32x4 pt;
; #pragma unroll
;             for (int e = 0; e < 4; ++e) pt[e] = __shfl_xor(v[e], 2);
;             if (j < 4) {
; #pragma unroll
;                 for (int e = 0; e < 4; ++e) v[e] = (j < 2) ? v[e] * ci[e] - pt[e] * si[e] : v[e] * ci[e] + pt[e] * si[e];
;             }
;             u32x2 o; o.x = cvt_pk_bf16(v[0], v[1]); o.y = cvt_pk_bf16(v[2], v[3]);
;             if (it < 4) *(u32x2*)(QIb + (size_t)tok * 1024 + head * 64 + 4 * j) = o;
;             else if (lane < 16) *(u32x2*)(KIb + (size_t)tok * 64 + 4 * j) = o;
;         }
;         if (lane < 16) { const float* rt = rawt + (size_t)tok * 256 + 64 + lane; WI[(size_t)tok * 16 + lane] = (rt[0] + rt[(size_t)T * 256] + rt[(size_t)2 * T * 256] + rt[(size_t)3 * T * 256]) * 0.03125f; }
.LBB0_772:
	s_or_b64 exec, exec, s[22:23]
	v_cvt_pk_bf16_f32 v54, v54, v55
	v_cvt_pk_bf16_f32 v55, v52, v53
	global_store_dwordx2 v[50:51], v[54:55], off offset:-512
	s_waitcnt lgkmcnt(0)
	v_mov_b64_e32 v[56:57], v[104:105]
	v_lshlrev_b32_e32 v52, 16, v57
	v_and_b32_e32 v53, 0xffff0000, v57
	v_lshlrev_b32_e32 v54, 16, v56
	v_and_b32_e32 v55, 0xffff0000, v56
	ds_bpermute_b32 v58, v66, v54
	ds_bpermute_b32 v59, v66, v55
	ds_bpermute_b32 v56, v66, v52
	ds_bpermute_b32 v57, v66, v53
	s_and_saveexec_b64 s[22:23], s[12:13]
	s_cbranch_execz .LBB0_774
	s_waitcnt lgkmcnt(2)
	v_pk_mul_f32 v[58:59], v[46:47], v[58:59]
	s_waitcnt lgkmcnt(0)
	v_pk_mul_f32 v[56:57], v[48:49], v[56:57]
	v_cndmask_b32_e64 v59, v59, -v59, s[14:15]
	v_cndmask_b32_e64 v58, v58, -v58, s[14:15]
	v_cndmask_b32_e64 v57, v57, -v57, s[14:15]
	v_cndmask_b32_e64 v56, v56, -v56, s[14:15]
	v_pk_fma_f32 v[54:55], v[42:43], v[54:55], v[58:59]
	v_pk_fma_f32 v[52:53], v[44:45], v[52:53], v[56:57]
.LBB0_774:
	s_or_b64 exec, exec, s[22:23]
	v_cvt_pk_bf16_f32 v54, v54, v55
	v_cvt_pk_bf16_f32 v55, v52, v53
	global_store_dwordx2 v[50:51], v[54:55], off
	v_mov_b64_e32 v[54:55], v[106:107]
	v_lshlrev_b32_e32 v40, 16, v55
	v_and_b32_e32 v41, 0xffff0000, v55
	v_lshlrev_b32_e32 v52, 16, v54
	v_and_b32_e32 v53, 0xffff0000, v54
	s_waitcnt lgkmcnt(1)
	ds_bpermute_b32 v56, v66, v52
	s_waitcnt lgkmcnt(1)
	ds_bpermute_b32 v57, v66, v53
	ds_bpermute_b32 v54, v66, v40
	ds_bpermute_b32 v55, v66, v41
	s_and_saveexec_b64 s[22:23], s[12:13]
	s_cbranch_execz .LBB0_776
	s_waitcnt lgkmcnt(2)
	v_pk_mul_f32 v[56:57], v[46:47], v[56:57]
	s_waitcnt lgkmcnt(0)
	v_pk_mul_f32 v[54:55], v[48:49], v[54:55]
	v_cndmask_b32_e64 v57, v57, -v57, s[14:15]
	v_cndmask_b32_e64 v56, v56, -v56, s[14:15]
	v_cndmask_b32_e64 v55, v55, -v55, s[14:15]
	v_cndmask_b32_e64 v54, v54, -v54, s[14:15]
	v_pk_fma_f32 v[52:53], v[42:43], v[52:53], v[56:57]
	v_pk_fma_f32 v[40:41], v[44:45], v[40:41], v[54:55]
.LBB0_776:
	s_or_b64 exec, exec, s[22:23]
	v_lshl_add_u64 v[58:59], s[2:3], 0, v[22:23]
	v_cvt_pk_bf16_f32 v52, v52, v53
	v_cvt_pk_bf16_f32 v53, v40, v41
	v_add_co_u32_e32 v40, vcc, 0x27f04000, v58
	global_store_dwordx2 v[50:51], v[52:53], off offset:512
	s_nop 0
	v_addc_co_u32_e32 v41, vcc, 0, v59, vcc
	v_mov_b64_e32 v[50:51], v[112:113]
	v_mov_b64_e32 v[52:53], v[114:115]
	v_add_co_u32_e32 v40, vcc, 0x28704000, v58
	s_nop 1
	v_addc_co_u32_e32 v41, vcc, 0, v59, vcc
	s_waitcnt lgkmcnt(0)
	v_mov_b64_e32 v[54:55], v[116:117]
	v_mov_b64_e32 v[56:57], v[118:119]
	v_pk_add_f32 v[54:55], v[50:51], v[54:55]
	v_add_co_u32_e32 v50, vcc, 0x28f04000, v58
	v_pk_add_f32 v[40:41], v[52:53], v[56:57]
	s_nop 0
	v_addc_co_u32_e32 v51, vcc, 0, v59, vcc
	v_mov_b64_e32 v[50:51], v[120:121]
	v_mov_b64_e32 v[52:53], v[122:123]
	v_pk_add_f32 v[54:55], v[54:55], v[50:51]
	v_add_co_u32_e32 v50, vcc, 0x29704000, v58
	v_pk_add_f32 v[40:41], v[40:41], v[52:53]
	s_nop 0
	v_addc_co_u32_e32 v51, vcc, 0, v59, vcc
	v_mov_b64_e32 v[50:51], v[124:125]
	v_mov_b64_e32 v[52:53], v[126:127]
	v_pk_add_f32 v[40:41], v[40:41], v[52:53]
	v_pk_add_f32 v[50:51], v[54:55], v[50:51]
	ds_bpermute_b32 v54, v66, v50
	ds_bpermute_b32 v55, v66, v51
	ds_bpermute_b32 v52, v66, v40
	ds_bpermute_b32 v53, v66, v41
	s_and_saveexec_b64 s[22:23], s[12:13]
	s_cbranch_execz .LBB0_778
	s_waitcnt lgkmcnt(2)
	v_pk_mul_f32 v[46:47], v[46:47], v[54:55]
	s_nop 0
	v_cndmask_b32_e64 v47, v47, -v47, s[14:15]
	v_cndmask_b32_e64 v46, v46, -v46, s[14:15]
	v_pk_fma_f32 v[50:51], v[42:43], v[50:51], v[46:47]
	s_waitcnt lgkmcnt(0)
	v_pk_mul_f32 v[42:43], v[48:49], v[52:53]
	s_nop 0
	v_cndmask_b32_e64 v43, v43, -v43, s[14:15]
	v_cndmask_b32_e64 v42, v42, -v42, s[14:15]
	v_pk_fma_f32 v[40:41], v[44:45], v[40:41], v[42:43]
.LBB0_778:
	s_or_b64 exec, exec, s[22:23]
	v_cvt_pk_bf16_f32 v42, v50, v51
	v_cvt_pk_bf16_f32 v43, v40, v41
	s_and_saveexec_b64 s[22:23], s[16:17]
	s_cbranch_execz .LBB0_747
	v_lshl_add_u64 v[40:41], s[2:3], 0, v[20:21]
	global_store_dwordx2 v[40:41], v[42:43], off
	v_lshl_add_u64 v[40:41], s[2:3], 0, v[24:25]
	v_add_co_u32_e32 v42, vcc, 0x27f04000, v40
	s_nop 1
	v_addc_co_u32_e32 v43, vcc, 0, v41, vcc
	v_mov_b32_e32 v44, v128
	v_add_co_u32_e32 v42, vcc, 0x28704000, v40
	s_nop 1
	v_addc_co_u32_e32 v43, vcc, 0, v41, vcc
	v_mov_b32_e32 v42, v129
	v_add_f32_e32 v44, v44, v42
	v_add_co_u32_e32 v42, vcc, 0x28f04000, v40
	s_nop 1
	v_addc_co_u32_e32 v43, vcc, 0, v41, vcc
	v_add_co_u32_e32 v40, vcc, 0x29704000, v40
	v_mov_b32_e32 v42, v130
	s_nop 0
	v_addc_co_u32_e32 v41, vcc, 0, v41, vcc
	v_mov_b32_e32 v40, v131
	v_add_f32_e32 v42, v44, v42
	v_add_f32_e32 v40, v42, v40
	v_mul_f32_e32 v42, 0x3d000000, v40
	v_lshl_add_u64 v[40:41], s[2:3], 0, v[18:19]
	global_store_dword v[40:41], v42, off
	s_branch .LBB0_747
